# barrier poll back-off: s_sleep 4 -> 1 in the two XCD-level wait loops of the grid barrier (on top of v49 stack)
# baseline (speedup 1.0000x reference)
; DEVI unsigned xb_ld(unsigned* p) { return __hip_atomic_load(p, __ATOMIC_RELAXED, __HIP_MEMORY_SCOPE_AGENT); }
; DEVI unsigned xb_add(unsigned* p, unsigned v) { return __hip_atomic_fetch_add(p, v, __ATOMIC_RELAXED, __HIP_MEMORY_SCOPE_AGENT); }
; #define XB_SPIN(cond, bar) do { unsigned _sp = 0; while (cond) { __builtin_amdgcn_s_sleep(4); \
;     if ((++_sp & 255u) == 0u) { if (xb_ld(&(bar)[XB_TMO])) break; if (_sp > XB_SPIN_CAP) { atomicAdd(&(bar)[XB_TMO], 1u); break; } } } } while (0)
; DEVI void xcd_barrier(const XcdBarrier& b) {
;     ...
;       else XB_SPIN(xb_ld(&bar[XB_TOPGEN]) == tg, bar);
;       __builtin_amdgcn_fence(__ATOMIC_ACQUIRE, "agent");
;       xb_add(&bar[XB_XGEN(b.x)], 1u);
;       asm volatile("s_waitcnt vmcnt(0)" ::: "memory");
;     } else {
;       XB_SPIN(xb_ld(&bar[XB_XGEN(b.x)]) == gen, bar);
.LBB0_803:
	s_and_b32 s14, s18, 0xff
	s_mov_b64 s[12:13], -1
	s_cmp_lg_u32 s14, 0
	s_mov_b64 s[16:17], -1
	s_sleep 1
	s_cbranch_scc0 .LBB0_806
	s_and_b64 vcc, exec, s[16:17]
	s_cbranch_vccz .LBB0_802
